# v100 with the P4 K-order reversal selected by XCD parity (bx bit 0) instead of row-panel parity (bit 3): every XCD keeps one K order
# baseline (speedup 1.0000x reference)
.LBB0_511:
	s_mov_b32 s98, 32
	s_movk_i32 s99, 0x1000
	s_movk_i32 s100, 0x1700
	s_movk_i32 s101, 0x1700
	v_readlane_b32 s0, v254, 2
	s_bitcmp1_b32 s0, 0
	s_cbranch_scc0 .Lp4_norev
	s_mov_b32 s98, 16
	s_mov_b32 s99, 0xfffff000
	s_movk_i32 s100, 0x700
	s_mov_b32 s101, 0xffffff00
	s_mov_b32 s0, s14
	s_mov_b32 s14, s38
	s_mov_b32 s38, s0
	s_mov_b32 s0, s15
	s_mov_b32 s15, s39
	s_mov_b32 s39, s0

.LBB0_986:
	s_ashr_i32 s0, s3, 3
	s_add_i32 s0, s5, s0
	s_ashr_i32 s1, s0, 31
	s_lshr_b32 s1, s1, 26
	s_add_i32 s1, s0, s1
	s_ashr_i32 s3, s1, 6
	s_andn2_b32 s1, s1, 63
	s_sub_i32 s0, s0, s1
	s_bfe_i32 s1, s0, 0x80000
	s_bfe_u32 s1, s1, 0x3000c
	s_add_i32 s1, s0, s1
	s_bfe_i32 s4, s1, 0x80000
	s_and_b32 s1, s1, 0xf8
	s_sub_i32 s0, s0, s1
	s_lshl_b32 s3, s3, 3
	s_sext_i32_i16 s4, s4
	s_sext_i32_i8 s0, s0
	s_lshr_b32 s37, s4, 3
	s_add_i32 s3, s3, s0
	s_cmp_gt_i32 s3, 0
	s_cselect_b64 vcc, -1, 0
	s_lshl_b32 s29, s3, 2
	s_or_b32 s38, s29, 2
	s_lshl_b32 s39, s3, 8
	s_add_u32 s12, s20, 0x5800
	s_addc_u32 s13, s21, 0
	s_waitcnt vmcnt(35)
	v_cndmask_b32_e64 v2, 0, 1.0, vcc
	s_add_u32 s16, s18, 0x5800
	v_lshlrev_b32_e32 v148, 3, v0
	s_waitcnt vmcnt(32)
	v_mov_b32_e32 v3, v2
	s_mov_b64 s[6:7], 0x5800
	s_addc_u32 s17, s19, 0
	s_mov_b64 s[10:11], 0
	s_movk_i32 s40, 0x2bf
	s_mov_b32 s41, 0xb000
	s_waitcnt vmcnt(30) lgkmcnt(1)
	v_mov_b64_e32 v[4:5], s[44:45]
	s_movk_i32 s42, 0x2c0
	s_waitcnt vmcnt(28) lgkmcnt(0)
	v_mov_b32_e32 v7, 0
	s_mov_b64 s[22:23], 0xb000
	s_mov_b64 s[30:31], 0x16000
	s_mov_b32 s43, 0x16000
	v_mov_b32_e32 v8, v2
	s_waitcnt vmcnt(26)
	v_mov_b32_e32 v9, v2
	s_movk_i32 s46, 0x5000
	s_movk_i32 s47, 0x2c00
	s_waitcnt vmcnt(24)
	v_mov_b64_e32 v[10:11], s[54:55]
	s_movk_i32 s48, 0x37f
	v_mov_b32_e32 v1, v148
	s_waitcnt vmcnt(21)
	v_mov_b32_e32 v16, v0
	v_readlane_b32 s60, v254, 2
	v_readlane_b32 s62, v254, 0
	v_readlane_b32 s63, v254, 1
	s_sub_u32 s62, s62, 0xc8
	s_subb_u32 s63, s63, 0
	s_load_dwordx4 s[64:67], s[62:63], 0x98
	s_and_b32 s61, s60, 7
	s_lshr_b32 s59, s60, 3
	s_lshl_b32 s61, s61, 5
	s_add_i32 s61, s61, s59
	s_bfe_u32 s98, s61, 0x30003
	s_lshr_b32 s59, s61, 6
	s_and_b32 s61, s61, 7
	s_lshl_b32 s59, s59, 3
	s_add_i32 s60, s59, s61
	s_cmp_lg_u32 s60, 0
	s_cselect_b32 s74, 1.0, 0
	s_mov_b32 s75, s74
	s_mov_b32 s68, 0x3d922279
	s_mov_b32 s70, 0x3fcc422a
	s_mov_b32 s72, 0xbfb8aa3b
	s_lshl_b32 s59, s60, 2
	s_add_u32 s82, s26, 0x18500000
	s_addc_u32 s83, s27, 0
	s_add_i32 s61, s59, 1
	s_max_i32 s61, s61, 0
	s_mul_i32 s61, s61, 0xb000
	s_add_u32 s88, s82, s61
	s_addc_u32 s89, s83, 0
	s_add_i32 s61, s59, 0
	s_max_i32 s61, s61, 0
	s_mul_i32 s61, s61, 0xb000
	s_add_u32 s86, s82, s61
	s_addc_u32 s87, s83, 0
	s_add_i32 s61, s59, -1
	s_max_i32 s61, s61, 0
	s_mul_i32 s61, s61, 0xb000
	s_add_u32 s84, s82, s61
	s_addc_u32 s85, s83, 0
	s_add_i32 s61, s59, -2
	s_max_i32 s61, s61, 0
	s_mul_i32 s61, s61, 0xb000
	s_add_u32 s82, s82, s61
	s_addc_u32 s83, s83, 0
	s_mul_i32 s61, s60, 0x2c0000
	s_add_u32 s90, s26, 0x7d00000
	s_addc_u32 s91, s27, 0
	s_add_u32 s90, s90, s61
	s_addc_u32 s91, s91, 0
	s_add_u32 s92, s90, 0x2c00
	s_addc_u32 s93, s91, 0
	s_waitcnt lgkmcnt(0)
	s_add_u32 s38, s64, 0x0
	s_addc_u32 s39, s65, 0
	s_add_u32 s40, s64, 0xb000
	s_addc_u32 s41, s65, 0
	s_add_u32 s42, s64, 0x16000
	s_addc_u32 s43, s65, 0
	v_lshlrev_b32_e32 v2, 5, v0
	v_add_u32_e32 v3, 0x5800, v2
	v_lshlrev_b32_e32 v4, 4, v0
	global_load_dwordx4 v[8:11], v2, s[66:67]
	global_load_dwordx4 v[12:15], v2, s[38:39]
	global_load_dwordx4 v[16:19], v2, s[40:41]
	global_load_dwordx4 v[20:23], v2, s[42:43]
	global_load_dwordx4 v[24:27], v2, s[82:83]
	global_load_dwordx4 v[28:31], v2, s[84:85]
	global_load_dwordx4 v[32:35], v2, s[86:87]
	global_load_dwordx4 v[36:39], v2, s[88:89]
	global_load_dwordx4 v[40:43], v2, s[66:67] offset:16
	global_load_dwordx4 v[44:47], v2, s[38:39] offset:16
	global_load_dwordx4 v[48:51], v2, s[40:41] offset:16
	global_load_dwordx4 v[52:55], v2, s[42:43] offset:16
	global_load_dwordx4 v[56:59], v2, s[82:83] offset:16
	global_load_dwordx4 v[60:63], v2, s[84:85] offset:16
	global_load_dwordx4 v[64:67], v2, s[86:87] offset:16
	global_load_dwordx4 v[68:71], v2, s[88:89] offset:16
	global_load_dwordx4 v[72:75], v3, s[66:67]
	global_load_dwordx4 v[76:79], v3, s[38:39]
	global_load_dwordx4 v[80:83], v3, s[40:41]
	global_load_dwordx4 v[84:87], v3, s[42:43]
	global_load_dwordx4 v[88:91], v3, s[82:83]
	global_load_dwordx4 v[92:95], v3, s[84:85]
	global_load_dwordx4 v[96:99], v3, s[86:87]
	global_load_dwordx4 v[100:103], v3, s[88:89]
	global_load_dwordx4 v[104:107], v3, s[66:67] offset:16
	global_load_dwordx4 v[108:111], v3, s[38:39] offset:16
	global_load_dwordx4 v[112:115], v3, s[40:41] offset:16
	global_load_dwordx4 v[116:119], v3, s[42:43] offset:16
	global_load_dwordx4 v[120:123], v3, s[82:83] offset:16
	global_load_dwordx4 v[124:127], v3, s[84:85] offset:16
	global_load_dwordx4 v[128:131], v3, s[86:87] offset:16
	global_load_dwordx4 v[132:135], v3, s[88:89] offset:16
	s_waitcnt vmcnt(0)
	v_pk_mul_f32 v[136:137], v[12:13], s[74:75] op_sel_hi:[1,0]
	v_pk_mul_f32 v[140:141], v[16:17], s[74:75] op_sel_hi:[1,0]
	v_pk_mul_f32 v[138:139], v[14:15], s[74:75] op_sel_hi:[1,0]
	v_pk_mul_f32 v[142:143], v[18:19], s[74:75] op_sel_hi:[1,0]
	v_pk_fma_f32 v[24:25], v[136:137], v[24:25], v[8:9]
	v_pk_fma_f32 v[8:9], v[136:137], v[28:29], v[8:9]
	v_pk_fma_f32 v[26:27], v[138:139], v[26:27], v[10:11]
	v_pk_fma_f32 v[10:11], v[138:139], v[30:31], v[10:11]
	v_pk_fma_f32 v[24:25], v[140:141], v[28:29], v[24:25]
	v_pk_fma_f32 v[8:9], v[16:17], v[32:33], v[8:9]
	v_pk_fma_f32 v[26:27], v[142:143], v[30:31], v[26:27]
	v_pk_fma_f32 v[10:11], v[18:19], v[34:35], v[10:11]
	v_pk_fma_f32 v[24:25], v[20:21], v[32:33], v[24:25]
	v_pk_fma_f32 v[8:9], v[20:21], v[36:37], v[8:9]
	v_pk_fma_f32 v[26:27], v[22:23], v[34:35], v[26:27]
	v_pk_fma_f32 v[10:11], v[22:23], v[38:39], v[10:11]
	v_pk_mul_f32 v[136:137], v[44:45], s[74:75] op_sel_hi:[1,0]
	v_pk_mul_f32 v[140:141], v[48:49], s[74:75] op_sel_hi:[1,0]
	v_pk_mul_f32 v[138:139], v[46:47], s[74:75] op_sel_hi:[1,0]
	v_pk_mul_f32 v[142:143], v[50:51], s[74:75] op_sel_hi:[1,0]
	v_pk_fma_f32 v[56:57], v[136:137], v[56:57], v[40:41]
	v_pk_fma_f32 v[40:41], v[136:137], v[60:61], v[40:41]
	v_pk_fma_f32 v[58:59], v[138:139], v[58:59], v[42:43]
	v_pk_fma_f32 v[42:43], v[138:139], v[62:63], v[42:43]
	v_pk_fma_f32 v[56:57], v[140:141], v[60:61], v[56:57]
	v_pk_fma_f32 v[40:41], v[48:49], v[64:65], v[40:41]
	v_pk_fma_f32 v[58:59], v[142:143], v[62:63], v[58:59]
	v_pk_fma_f32 v[42:43], v[50:51], v[66:67], v[42:43]
	v_pk_fma_f32 v[56:57], v[52:53], v[64:65], v[56:57]
	v_pk_fma_f32 v[40:41], v[52:53], v[68:69], v[40:41]
	v_pk_fma_f32 v[58:59], v[54:55], v[66:67], v[58:59]
	v_pk_fma_f32 v[42:43], v[54:55], v[70:71], v[42:43]
	v_pk_mul_f32 v[136:137], v[76:77], s[74:75] op_sel_hi:[1,0]
	v_pk_mul_f32 v[140:141], v[80:81], s[74:75] op_sel_hi:[1,0]
	v_pk_mul_f32 v[138:139], v[78:79], s[74:75] op_sel_hi:[1,0]
	v_pk_mul_f32 v[142:143], v[82:83], s[74:75] op_sel_hi:[1,0]
	v_pk_fma_f32 v[88:89], v[136:137], v[88:89], v[72:73]
	v_pk_fma_f32 v[72:73], v[136:137], v[92:93], v[72:73]
	v_pk_fma_f32 v[90:91], v[138:139], v[90:91], v[74:75]
	v_pk_fma_f32 v[74:75], v[138:139], v[94:95], v[74:75]
	v_pk_fma_f32 v[88:89], v[140:141], v[92:93], v[88:89]
	v_pk_fma_f32 v[72:73], v[80:81], v[96:97], v[72:73]
	v_pk_fma_f32 v[90:91], v[142:143], v[94:95], v[90:91]
	v_pk_fma_f32 v[74:75], v[82:83], v[98:99], v[74:75]
	v_pk_fma_f32 v[88:89], v[84:85], v[96:97], v[88:89]
	v_pk_fma_f32 v[72:73], v[84:85], v[100:101], v[72:73]
	v_pk_fma_f32 v[90:91], v[86:87], v[98:99], v[90:91]
	v_pk_fma_f32 v[74:75], v[86:87], v[102:103], v[74:75]
	v_pk_mul_f32 v[136:137], v[108:109], s[74:75] op_sel_hi:[1,0]
	v_pk_mul_f32 v[140:141], v[112:113], s[74:75] op_sel_hi:[1,0]
	v_pk_mul_f32 v[138:139], v[110:111], s[74:75] op_sel_hi:[1,0]
	v_pk_mul_f32 v[142:143], v[114:115], s[74:75] op_sel_hi:[1,0]
	v_pk_fma_f32 v[120:121], v[136:137], v[120:121], v[104:105]
	v_pk_fma_f32 v[104:105], v[136:137], v[124:125], v[104:105]
	v_pk_fma_f32 v[122:123], v[138:139], v[122:123], v[106:107]
	v_pk_fma_f32 v[106:107], v[138:139], v[126:127], v[106:107]
	v_pk_fma_f32 v[120:121], v[140:141], v[124:125], v[120:121]
	v_pk_fma_f32 v[104:105], v[112:113], v[128:129], v[104:105]
	v_pk_fma_f32 v[122:123], v[142:143], v[126:127], v[122:123]
	v_pk_fma_f32 v[106:107], v[114:115], v[130:131], v[106:107]
	v_pk_fma_f32 v[120:121], v[116:117], v[128:129], v[120:121]
	v_pk_fma_f32 v[104:105], v[116:117], v[132:133], v[104:105]
	v_pk_fma_f32 v[122:123], v[118:119], v[130:131], v[122:123]
	v_pk_fma_f32 v[106:107], v[118:119], v[134:135], v[106:107]
	v_pk_mul_f32 v[144:145], v[24:25], s[68:69] op_sel_hi:[1,0]
	v_pk_fma_f32 v[144:145], v[144:145], v[24:25], s[70:71] op_sel_hi:[1,1,0]
	v_pk_mul_f32 v[144:145], v[24:25], v[144:145]
	v_pk_mul_f32 v[144:145], v[144:145], s[72:73] op_sel_hi:[1,0]
	v_exp_f32_e32 v144, v144
	v_exp_f32_e32 v145, v145
	s_nop 0
	v_pk_add_f32 v[144:145], v[144:145], 1.0 op_sel_hi:[1,0]
	v_rcp_f32_e32 v144, v144
	v_rcp_f32_e32 v145, v145
	s_nop 0
	v_pk_mul_f32 v[144:145], v[24:25], v[144:145]
	v_pk_mul_f32 v[144:145], v[144:145], v[88:89]
	v_cvt_pk_bf16_f32 v150, v144, v145
	v_pk_mul_f32 v[144:145], v[26:27], s[68:69] op_sel_hi:[1,0]
	v_pk_fma_f32 v[144:145], v[144:145], v[26:27], s[70:71] op_sel_hi:[1,1,0]
	v_pk_mul_f32 v[144:145], v[26:27], v[144:145]
	v_pk_mul_f32 v[144:145], v[144:145], s[72:73] op_sel_hi:[1,0]
	v_exp_f32_e32 v144, v144
	v_exp_f32_e32 v145, v145
	s_nop 0
	v_pk_add_f32 v[144:145], v[144:145], 1.0 op_sel_hi:[1,0]
	v_rcp_f32_e32 v144, v144
	v_rcp_f32_e32 v145, v145
	s_nop 0
	v_pk_mul_f32 v[144:145], v[26:27], v[144:145]
	v_pk_mul_f32 v[144:145], v[144:145], v[90:91]
	v_cvt_pk_bf16_f32 v151, v144, v145
	v_pk_mul_f32 v[144:145], v[56:57], s[68:69] op_sel_hi:[1,0]
	v_pk_fma_f32 v[144:145], v[144:145], v[56:57], s[70:71] op_sel_hi:[1,1,0]
	v_pk_mul_f32 v[144:145], v[56:57], v[144:145]
	v_pk_mul_f32 v[144:145], v[144:145], s[72:73] op_sel_hi:[1,0]
	v_exp_f32_e32 v144, v144
	v_exp_f32_e32 v145, v145
	s_nop 0
	v_pk_add_f32 v[144:145], v[144:145], 1.0 op_sel_hi:[1,0]
	v_rcp_f32_e32 v144, v144
	v_rcp_f32_e32 v145, v145
	s_nop 0
	v_pk_mul_f32 v[144:145], v[56:57], v[144:145]
	v_pk_mul_f32 v[144:145], v[144:145], v[120:121]
	v_cvt_pk_bf16_f32 v152, v144, v145
	v_pk_mul_f32 v[144:145], v[58:59], s[68:69] op_sel_hi:[1,0]
	v_pk_fma_f32 v[144:145], v[144:145], v[58:59], s[70:71] op_sel_hi:[1,1,0]
	v_pk_mul_f32 v[144:145], v[58:59], v[144:145]
	v_pk_mul_f32 v[144:145], v[144:145], s[72:73] op_sel_hi:[1,0]
	v_exp_f32_e32 v144, v144
	v_exp_f32_e32 v145, v145
	s_nop 0
	v_pk_add_f32 v[144:145], v[144:145], 1.0 op_sel_hi:[1,0]
	v_rcp_f32_e32 v144, v144
	v_rcp_f32_e32 v145, v145
	s_nop 0
	v_pk_mul_f32 v[144:145], v[58:59], v[144:145]
	v_pk_mul_f32 v[144:145], v[144:145], v[122:123]
	v_cvt_pk_bf16_f32 v153, v144, v145
	global_store_dwordx4 v4, v[150:153], s[90:91]
	s_nop 1
	v_pk_mul_f32 v[144:145], v[8:9], s[68:69] op_sel_hi:[1,0]
	v_pk_fma_f32 v[144:145], v[144:145], v[8:9], s[70:71] op_sel_hi:[1,1,0]
	v_pk_mul_f32 v[144:145], v[8:9], v[144:145]
	v_pk_mul_f32 v[144:145], v[144:145], s[72:73] op_sel_hi:[1,0]
	v_exp_f32_e32 v144, v144
	v_exp_f32_e32 v145, v145
	s_nop 0
	v_pk_add_f32 v[144:145], v[144:145], 1.0 op_sel_hi:[1,0]
	v_rcp_f32_e32 v144, v144
	v_rcp_f32_e32 v145, v145
	s_nop 0
	v_pk_mul_f32 v[144:145], v[8:9], v[144:145]
	v_pk_mul_f32 v[144:145], v[144:145], v[72:73]
	v_cvt_pk_bf16_f32 v150, v144, v145
	v_pk_mul_f32 v[144:145], v[10:11], s[68:69] op_sel_hi:[1,0]
	v_pk_fma_f32 v[144:145], v[144:145], v[10:11], s[70:71] op_sel_hi:[1,1,0]
	v_pk_mul_f32 v[144:145], v[10:11], v[144:145]
	v_pk_mul_f32 v[144:145], v[144:145], s[72:73] op_sel_hi:[1,0]
	v_exp_f32_e32 v144, v144
	v_exp_f32_e32 v145, v145
	s_nop 0
	v_pk_add_f32 v[144:145], v[144:145], 1.0 op_sel_hi:[1,0]
	v_rcp_f32_e32 v144, v144
	v_rcp_f32_e32 v145, v145
	s_nop 0
	v_pk_mul_f32 v[144:145], v[10:11], v[144:145]
	v_pk_mul_f32 v[144:145], v[144:145], v[74:75]
	v_cvt_pk_bf16_f32 v151, v144, v145
	v_pk_mul_f32 v[144:145], v[40:41], s[68:69] op_sel_hi:[1,0]
	v_pk_fma_f32 v[144:145], v[144:145], v[40:41], s[70:71] op_sel_hi:[1,1,0]
	v_pk_mul_f32 v[144:145], v[40:41], v[144:145]
	v_pk_mul_f32 v[144:145], v[144:145], s[72:73] op_sel_hi:[1,0]
	v_exp_f32_e32 v144, v144
	v_exp_f32_e32 v145, v145
	s_nop 0
	v_pk_add_f32 v[144:145], v[144:145], 1.0 op_sel_hi:[1,0]
	v_rcp_f32_e32 v144, v144
	v_rcp_f32_e32 v145, v145
	s_nop 0
	v_pk_mul_f32 v[144:145], v[40:41], v[144:145]
	v_pk_mul_f32 v[144:145], v[144:145], v[104:105]
	v_cvt_pk_bf16_f32 v152, v144, v145
	v_pk_mul_f32 v[144:145], v[42:43], s[68:69] op_sel_hi:[1,0]
	v_pk_fma_f32 v[144:145], v[144:145], v[42:43], s[70:71] op_sel_hi:[1,1,0]
	v_pk_mul_f32 v[144:145], v[42:43], v[144:145]
	v_pk_mul_f32 v[144:145], v[144:145], s[72:73] op_sel_hi:[1,0]
	v_exp_f32_e32 v144, v144
	v_exp_f32_e32 v145, v145
	s_nop 0
	v_pk_add_f32 v[144:145], v[144:145], 1.0 op_sel_hi:[1,0]
	v_rcp_f32_e32 v144, v144
	v_rcp_f32_e32 v145, v145
	s_nop 0
	v_pk_mul_f32 v[144:145], v[42:43], v[144:145]
	v_pk_mul_f32 v[144:145], v[144:145], v[106:107]
	v_cvt_pk_bf16_f32 v153, v144, v145
	global_store_dwordx4 v4, v[150:153], s[92:93]
	s_nop 1
	v_readfirstlane_b32 s59, v0
	s_lshr_b32 s59, s59, 6
	s_cmp_gt_u32 s59, 2
	s_cbranch_scc1 .Lhook_done
	v_add_u32_e32 v2, 0x4000, v2
	v_add_u32_e32 v3, 0x4000, v3
	v_add_u32_e32 v4, 0x2000, v4
	global_load_dwordx4 v[8:11], v2, s[66:67]
	global_load_dwordx4 v[12:15], v2, s[38:39]
	global_load_dwordx4 v[16:19], v2, s[40:41]
	global_load_dwordx4 v[20:23], v2, s[42:43]
	global_load_dwordx4 v[24:27], v2, s[82:83]
	global_load_dwordx4 v[28:31], v2, s[84:85]
	global_load_dwordx4 v[32:35], v2, s[86:87]
	global_load_dwordx4 v[36:39], v2, s[88:89]
	global_load_dwordx4 v[40:43], v2, s[66:67] offset:16
	global_load_dwordx4 v[44:47], v2, s[38:39] offset:16
	global_load_dwordx4 v[48:51], v2, s[40:41] offset:16
	global_load_dwordx4 v[52:55], v2, s[42:43] offset:16
	global_load_dwordx4 v[56:59], v2, s[82:83] offset:16
	global_load_dwordx4 v[60:63], v2, s[84:85] offset:16
	global_load_dwordx4 v[64:67], v2, s[86:87] offset:16
	global_load_dwordx4 v[68:71], v2, s[88:89] offset:16
	global_load_dwordx4 v[72:75], v3, s[66:67]
	global_load_dwordx4 v[76:79], v3, s[38:39]
	global_load_dwordx4 v[80:83], v3, s[40:41]
	global_load_dwordx4 v[84:87], v3, s[42:43]
	global_load_dwordx4 v[88:91], v3, s[82:83]
	global_load_dwordx4 v[92:95], v3, s[84:85]
	global_load_dwordx4 v[96:99], v3, s[86:87]
	global_load_dwordx4 v[100:103], v3, s[88:89]
	global_load_dwordx4 v[104:107], v3, s[66:67] offset:16
	global_load_dwordx4 v[108:111], v3, s[38:39] offset:16
	global_load_dwordx4 v[112:115], v3, s[40:41] offset:16
	global_load_dwordx4 v[116:119], v3, s[42:43] offset:16
	global_load_dwordx4 v[120:123], v3, s[82:83] offset:16
	global_load_dwordx4 v[124:127], v3, s[84:85] offset:16
	global_load_dwordx4 v[128:131], v3, s[86:87] offset:16
	global_load_dwordx4 v[132:135], v3, s[88:89] offset:16
	s_waitcnt vmcnt(0)
	v_pk_mul_f32 v[136:137], v[12:13], s[74:75] op_sel_hi:[1,0]
	v_pk_mul_f32 v[140:141], v[16:17], s[74:75] op_sel_hi:[1,0]
	v_pk_mul_f32 v[138:139], v[14:15], s[74:75] op_sel_hi:[1,0]
	v_pk_mul_f32 v[142:143], v[18:19], s[74:75] op_sel_hi:[1,0]
	v_pk_fma_f32 v[24:25], v[136:137], v[24:25], v[8:9]
	v_pk_fma_f32 v[8:9], v[136:137], v[28:29], v[8:9]
	v_pk_fma_f32 v[26:27], v[138:139], v[26:27], v[10:11]
	v_pk_fma_f32 v[10:11], v[138:139], v[30:31], v[10:11]
	v_pk_fma_f32 v[24:25], v[140:141], v[28:29], v[24:25]
	v_pk_fma_f32 v[8:9], v[16:17], v[32:33], v[8:9]
	v_pk_fma_f32 v[26:27], v[142:143], v[30:31], v[26:27]
	v_pk_fma_f32 v[10:11], v[18:19], v[34:35], v[10:11]
	v_pk_fma_f32 v[24:25], v[20:21], v[32:33], v[24:25]
	v_pk_fma_f32 v[8:9], v[20:21], v[36:37], v[8:9]
	v_pk_fma_f32 v[26:27], v[22:23], v[34:35], v[26:27]
	v_pk_fma_f32 v[10:11], v[22:23], v[38:39], v[10:11]
	v_pk_mul_f32 v[136:137], v[44:45], s[74:75] op_sel_hi:[1,0]
	v_pk_mul_f32 v[140:141], v[48:49], s[74:75] op_sel_hi:[1,0]
	v_pk_mul_f32 v[138:139], v[46:47], s[74:75] op_sel_hi:[1,0]
	v_pk_mul_f32 v[142:143], v[50:51], s[74:75] op_sel_hi:[1,0]
	v_pk_fma_f32 v[56:57], v[136:137], v[56:57], v[40:41]
	v_pk_fma_f32 v[40:41], v[136:137], v[60:61], v[40:41]
	v_pk_fma_f32 v[58:59], v[138:139], v[58:59], v[42:43]
	v_pk_fma_f32 v[42:43], v[138:139], v[62:63], v[42:43]
	v_pk_fma_f32 v[56:57], v[140:141], v[60:61], v[56:57]
	v_pk_fma_f32 v[40:41], v[48:49], v[64:65], v[40:41]
	v_pk_fma_f32 v[58:59], v[142:143], v[62:63], v[58:59]
	v_pk_fma_f32 v[42:43], v[50:51], v[66:67], v[42:43]
	v_pk_fma_f32 v[56:57], v[52:53], v[64:65], v[56:57]
	v_pk_fma_f32 v[40:41], v[52:53], v[68:69], v[40:41]
	v_pk_fma_f32 v[58:59], v[54:55], v[66:67], v[58:59]
	v_pk_fma_f32 v[42:43], v[54:55], v[70:71], v[42:43]
	v_pk_mul_f32 v[136:137], v[76:77], s[74:75] op_sel_hi:[1,0]
	v_pk_mul_f32 v[140:141], v[80:81], s[74:75] op_sel_hi:[1,0]
	v_pk_mul_f32 v[138:139], v[78:79], s[74:75] op_sel_hi:[1,0]
	v_pk_mul_f32 v[142:143], v[82:83], s[74:75] op_sel_hi:[1,0]
	v_pk_fma_f32 v[88:89], v[136:137], v[88:89], v[72:73]
	v_pk_fma_f32 v[72:73], v[136:137], v[92:93], v[72:73]
	v_pk_fma_f32 v[90:91], v[138:139], v[90:91], v[74:75]
	v_pk_fma_f32 v[74:75], v[138:139], v[94:95], v[74:75]
	v_pk_fma_f32 v[88:89], v[140:141], v[92:93], v[88:89]
	v_pk_fma_f32 v[72:73], v[80:81], v[96:97], v[72:73]
	v_pk_fma_f32 v[90:91], v[142:143], v[94:95], v[90:91]
	v_pk_fma_f32 v[74:75], v[82:83], v[98:99], v[74:75]
	v_pk_fma_f32 v[88:89], v[84:85], v[96:97], v[88:89]
	v_pk_fma_f32 v[72:73], v[84:85], v[100:101], v[72:73]
	v_pk_fma_f32 v[90:91], v[86:87], v[98:99], v[90:91]
	v_pk_fma_f32 v[74:75], v[86:87], v[102:103], v[74:75]
	v_pk_mul_f32 v[136:137], v[108:109], s[74:75] op_sel_hi:[1,0]
	v_pk_mul_f32 v[140:141], v[112:113], s[74:75] op_sel_hi:[1,0]
	v_pk_mul_f32 v[138:139], v[110:111], s[74:75] op_sel_hi:[1,0]
	v_pk_mul_f32 v[142:143], v[114:115], s[74:75] op_sel_hi:[1,0]
	v_pk_fma_f32 v[120:121], v[136:137], v[120:121], v[104:105]
	v_pk_fma_f32 v[104:105], v[136:137], v[124:125], v[104:105]
	v_pk_fma_f32 v[122:123], v[138:139], v[122:123], v[106:107]
	v_pk_fma_f32 v[106:107], v[138:139], v[126:127], v[106:107]
	v_pk_fma_f32 v[120:121], v[140:141], v[124:125], v[120:121]
	v_pk_fma_f32 v[104:105], v[112:113], v[128:129], v[104:105]
	v_pk_fma_f32 v[122:123], v[142:143], v[126:127], v[122:123]
	v_pk_fma_f32 v[106:107], v[114:115], v[130:131], v[106:107]
	v_pk_fma_f32 v[120:121], v[116:117], v[128:129], v[120:121]
	v_pk_fma_f32 v[104:105], v[116:117], v[132:133], v[104:105]
	v_pk_fma_f32 v[122:123], v[118:119], v[130:131], v[122:123]
	v_pk_fma_f32 v[106:107], v[118:119], v[134:135], v[106:107]
	v_pk_mul_f32 v[144:145], v[24:25], s[68:69] op_sel_hi:[1,0]
	v_pk_fma_f32 v[144:145], v[144:145], v[24:25], s[70:71] op_sel_hi:[1,1,0]
	v_pk_mul_f32 v[144:145], v[24:25], v[144:145]
	v_pk_mul_f32 v[144:145], v[144:145], s[72:73] op_sel_hi:[1,0]
	v_exp_f32_e32 v144, v144
	v_exp_f32_e32 v145, v145
	s_nop 0
	v_pk_add_f32 v[144:145], v[144:145], 1.0 op_sel_hi:[1,0]
	v_rcp_f32_e32 v144, v144
	v_rcp_f32_e32 v145, v145
	s_nop 0
	v_pk_mul_f32 v[144:145], v[24:25], v[144:145]
	v_pk_mul_f32 v[144:145], v[144:145], v[88:89]
	v_cvt_pk_bf16_f32 v150, v144, v145
	v_pk_mul_f32 v[144:145], v[26:27], s[68:69] op_sel_hi:[1,0]
	v_pk_fma_f32 v[144:145], v[144:145], v[26:27], s[70:71] op_sel_hi:[1,1,0]
	v_pk_mul_f32 v[144:145], v[26:27], v[144:145]
	v_pk_mul_f32 v[144:145], v[144:145], s[72:73] op_sel_hi:[1,0]
	v_exp_f32_e32 v144, v144
	v_exp_f32_e32 v145, v145
	s_nop 0
	v_pk_add_f32 v[144:145], v[144:145], 1.0 op_sel_hi:[1,0]
	v_rcp_f32_e32 v144, v144
	v_rcp_f32_e32 v145, v145
	s_nop 0
	v_pk_mul_f32 v[144:145], v[26:27], v[144:145]
	v_pk_mul_f32 v[144:145], v[144:145], v[90:91]
	v_cvt_pk_bf16_f32 v151, v144, v145
	v_pk_mul_f32 v[144:145], v[56:57], s[68:69] op_sel_hi:[1,0]
	v_pk_fma_f32 v[144:145], v[144:145], v[56:57], s[70:71] op_sel_hi:[1,1,0]
	v_pk_mul_f32 v[144:145], v[56:57], v[144:145]
	v_pk_mul_f32 v[144:145], v[144:145], s[72:73] op_sel_hi:[1,0]
	v_exp_f32_e32 v144, v144
	v_exp_f32_e32 v145, v145
	s_nop 0
	v_pk_add_f32 v[144:145], v[144:145], 1.0 op_sel_hi:[1,0]
	v_rcp_f32_e32 v144, v144
	v_rcp_f32_e32 v145, v145
	s_nop 0
	v_pk_mul_f32 v[144:145], v[56:57], v[144:145]
	v_pk_mul_f32 v[144:145], v[144:145], v[120:121]
	v_cvt_pk_bf16_f32 v152, v144, v145
	v_pk_mul_f32 v[144:145], v[58:59], s[68:69] op_sel_hi:[1,0]
	v_pk_fma_f32 v[144:145], v[144:145], v[58:59], s[70:71] op_sel_hi:[1,1,0]
	v_pk_mul_f32 v[144:145], v[58:59], v[144:145]
	v_pk_mul_f32 v[144:145], v[144:145], s[72:73] op_sel_hi:[1,0]
	v_exp_f32_e32 v144, v144
	v_exp_f32_e32 v145, v145
	s_nop 0
	v_pk_add_f32 v[144:145], v[144:145], 1.0 op_sel_hi:[1,0]
	v_rcp_f32_e32 v144, v144
	v_rcp_f32_e32 v145, v145
	s_nop 0
	v_pk_mul_f32 v[144:145], v[58:59], v[144:145]
	v_pk_mul_f32 v[144:145], v[144:145], v[122:123]
	v_cvt_pk_bf16_f32 v153, v144, v145
	global_store_dwordx4 v4, v[150:153], s[90:91]
	s_nop 1
	v_pk_mul_f32 v[144:145], v[8:9], s[68:69] op_sel_hi:[1,0]
	v_pk_fma_f32 v[144:145], v[144:145], v[8:9], s[70:71] op_sel_hi:[1,1,0]
	v_pk_mul_f32 v[144:145], v[8:9], v[144:145]
	v_pk_mul_f32 v[144:145], v[144:145], s[72:73] op_sel_hi:[1,0]
	v_exp_f32_e32 v144, v144
	v_exp_f32_e32 v145, v145
	s_nop 0
	v_pk_add_f32 v[144:145], v[144:145], 1.0 op_sel_hi:[1,0]
	v_rcp_f32_e32 v144, v144
	v_rcp_f32_e32 v145, v145
	s_nop 0
	v_pk_mul_f32 v[144:145], v[8:9], v[144:145]
	v_pk_mul_f32 v[144:145], v[144:145], v[72:73]
	v_cvt_pk_bf16_f32 v150, v144, v145
	v_pk_mul_f32 v[144:145], v[10:11], s[68:69] op_sel_hi:[1,0]
	v_pk_fma_f32 v[144:145], v[144:145], v[10:11], s[70:71] op_sel_hi:[1,1,0]
	v_pk_mul_f32 v[144:145], v[10:11], v[144:145]
	v_pk_mul_f32 v[144:145], v[144:145], s[72:73] op_sel_hi:[1,0]
	v_exp_f32_e32 v144, v144
	v_exp_f32_e32 v145, v145
	s_nop 0
	v_pk_add_f32 v[144:145], v[144:145], 1.0 op_sel_hi:[1,0]
	v_rcp_f32_e32 v144, v144
	v_rcp_f32_e32 v145, v145
	s_nop 0
	v_pk_mul_f32 v[144:145], v[10:11], v[144:145]
	v_pk_mul_f32 v[144:145], v[144:145], v[74:75]
	v_cvt_pk_bf16_f32 v151, v144, v145
	v_pk_mul_f32 v[144:145], v[40:41], s[68:69] op_sel_hi:[1,0]
	v_pk_fma_f32 v[144:145], v[144:145], v[40:41], s[70:71] op_sel_hi:[1,1,0]
	v_pk_mul_f32 v[144:145], v[40:41], v[144:145]
	v_pk_mul_f32 v[144:145], v[144:145], s[72:73] op_sel_hi:[1,0]
	v_exp_f32_e32 v144, v144
	v_exp_f32_e32 v145, v145
	s_nop 0
	v_pk_add_f32 v[144:145], v[144:145], 1.0 op_sel_hi:[1,0]
	v_rcp_f32_e32 v144, v144
	v_rcp_f32_e32 v145, v145
	s_nop 0
	v_pk_mul_f32 v[144:145], v[40:41], v[144:145]
	v_pk_mul_f32 v[144:145], v[144:145], v[104:105]
	v_cvt_pk_bf16_f32 v152, v144, v145
	v_pk_mul_f32 v[144:145], v[42:43], s[68:69] op_sel_hi:[1,0]
	v_pk_fma_f32 v[144:145], v[144:145], v[42:43], s[70:71] op_sel_hi:[1,1,0]
	v_pk_mul_f32 v[144:145], v[42:43], v[144:145]
	v_pk_mul_f32 v[144:145], v[144:145], s[72:73] op_sel_hi:[1,0]
	v_exp_f32_e32 v144, v144
	v_exp_f32_e32 v145, v145
	s_nop 0
	v_pk_add_f32 v[144:145], v[144:145], 1.0 op_sel_hi:[1,0]
	v_rcp_f32_e32 v144, v144
	v_rcp_f32_e32 v145, v145
	s_nop 0
	v_pk_mul_f32 v[144:145], v[42:43], v[144:145]
	v_pk_mul_f32 v[144:145], v[144:145], v[106:107]
	v_cvt_pk_bf16_f32 v153, v144, v145
	global_store_dwordx4 v4, v[150:153], s[92:93]
	s_nop 1
